# P3 W_in epilogue and P7 gate epilogue: all 8 row sum-of-squares loads issued at the epilogue head, per-row vmcnt(0) waits (behind stores/atomics) removed; plus P8 gate/MG batch prefetch, P0 rebalance
# speedup vs baseline: 1.0096x; 1.0053x over previous
; template <int NP> DI float row_rstd(const float* P, int row, float invn) {
;     if (NP == 0) return 1.0f;
;     return __builtin_amdgcn_rsqf(P[row] * invn + EPS);
; }
;     DI void operator()(const f32x4 (&acc)[2][2][4][2], const Unit& u, int wr, int wc, int fr, int fq) const {
;         const int row0 = u.pm * 256 + wr * 64 + fr, cw = wc * 32 + 8 * fq;
; #pragma unroll
;         for (int ai = 0; ai < 2; ++ai)
; #pragma unroll
;             for (int m = 0; m < 4; ++m) {
;                 const int row = row0 + ai * 128 + m * 16; const float rs = row_rstd<16>(P, row, 1.0f / 1024.0f);
; #pragma unroll
;                 for (int bj = 0; bj < 2; ++bj) {
;                     const int c128 = u.pn * 256 + bj * 128;
;                     float v[8];
; #pragma unroll
;                     for (int n = 0; n < 2; ++n)
; #pragma unroll
;                         for (int i = 0; i < 4; ++i) v[4 * n + i] = acc[ai][bj][m][n][i] * rs;
;                     if (c128 < 1024) {
.LBB0_635:
	v_lshl_add_u32 v154, s6, 8, v129
	v_ashrrev_i32_e32 v155, 31, v154
	v_lshl_add_u64 v[156:157], v[154:155], 2, s[52:53]
	global_load_dword v236, v[156:157], off
	global_load_dword v237, v[156:157], off offset:64
	global_load_dword v238, v[156:157], off offset:128
	global_load_dword v239, v[156:157], off offset:192
	global_load_dword v240, v[156:157], off offset:512
	global_load_dword v241, v[156:157], off offset:576
	global_load_dword v242, v[156:157], off offset:640
	global_load_dword v243, v[156:157], off offset:704
	s_lshl_b32 s94, s60, 8
	s_cmp_gt_i32 s60, 3
	s_cselect_b64 s[10:11], -1, 0
	s_mov_b64 s[44:45], s[72:73]
	s_mov_b64 s[72:73], s[84:85]
	s_mov_b64 s[86:87], s[18:19]
	s_mov_b64 s[6:7], -1
	v_mad_i64_i32 v[160:161], s[8:9], v154, s33, 0
	v_lshlrev_b64 v[158:159], 10, v[154:155]
	v_lshlrev_b64 v[164:165], 6, v[154:155]
	v_lshlrev_b64 v[162:163], 9, v[154:155]
	s_and_b64 vcc, exec, s[10:11]
	s_mov_b64 s[84:85], s[16:17]
	s_waitcnt vmcnt(0) lgkmcnt(0)
	v_fmamk_f32 v140, v236, 0x3a800000, v174
	v_rsq_f32_e32 v166, v140
	s_nop 0
	v_pk_mul_f32 v[168:169], v[124:125], v[166:167] op_sel_hi:[1,0]
	v_pk_mul_f32 v[126:127], v[126:127], v[166:167] op_sel_hi:[1,0]
	v_pk_mul_f32 v[124:125], v[120:121], v[166:167] op_sel_hi:[1,0]
	v_pk_mul_f32 v[122:123], v[122:123], v[166:167] op_sel_hi:[1,0]
	s_cbranch_vccz .LBB0_652
	s_cmpk_gt_u32 s94, 0x87f
	s_cbranch_scc1 .LBB0_651
	s_cmpk_gt_u32 s94, 0x57f
	s_cbranch_scc0 .LBB0_643
	s_cmpk_gt_u32 s94, 0x67f
	s_cbranch_scc0 .LBB0_640
	v_readlane_b32 s6, v248, 12
	v_readlane_b32 s7, v248, 13
	s_add_i32 s48, s94, 0xfffff980
	s_nop 0
	v_lshl_add_u64 v[120:121], s[6:7], 0, v[158:159]
	v_readlane_b32 s6, v248, 16
	v_readlane_b32 s7, v248, 17
	v_lshl_add_u64 v[170:171], s[48:49], 1, v[120:121]
	s_lshr_b32 s48, s48, 3
	v_lshl_add_u64 v[120:121], s[6:7], 0, v[164:165]
	v_lshl_add_u64 v[120:121], v[120:121], 0, s[48:49]
	s_lshl_b32 s48, s97, 2
	v_lshl_add_u64 v[120:121], v[120:121], 0, s[48:49]
	s_mov_b64 s[6:7], 0

;     DI void operator()(const f32x4 (&acc)[2][2][4][2], const Unit& u, int wr, int wc, int fr, int fq) const {
;     ...
;             for (int m = 0; m < 4; ++m) {
;                 const int row = row0 + ai * 128 + m * 16; const float rs = row_rstd<16>(P, row, 1.0f / 1024.0f);
; #pragma unroll
;                 for (int bj = 0; bj < 2; ++bj) {
;                     const int c128 = u.pn * 256 + bj * 128;
;                     float v[8];
; #pragma unroll
;                     for (int n = 0; n < 2; ++n)
; #pragma unroll
;                         for (int i = 0; i < 4; ++i) v[4 * n + i] = acc[ai][bj][m][n][i] * rs;
;                     if (c128 < 1024) {
.LBB0_683:
	s_waitcnt lgkmcnt(0)
	v_or_b32_e32 v114, 16, v154
	v_ashrrev_i32_e32 v115, 31, v114
	v_lshl_add_u64 v[112:113], v[114:115], 2, s[52:53]
	s_nop 0
	v_cndmask_b32_e64 v112, 0, 1, s[10:11]
	v_mad_i64_i32 v[116:117], s[6:7], v114, s33, 0
	v_cmp_ne_u32_e64 s[8:9], 1, v112
	v_lshlrev_b64 v[112:113], 10, v[114:115]
	v_lshlrev_b64 v[120:121], 6, v[114:115]
	s_andn2_b64 vcc, exec, s[10:11]
	s_mov_b64 s[6:7], -1
	s_waitcnt lgkmcnt(0)
	v_fmamk_f32 v118, v237, 0x3a800000, v174
	v_rsq_f32_e32 v122, v118
	v_lshlrev_b64 v[118:119], 9, v[114:115]
	v_pk_mul_f32 v[124:125], v[108:109], v[122:123] op_sel_hi:[1,0]
	v_pk_mul_f32 v[110:111], v[110:111], v[122:123] op_sel_hi:[1,0]
	v_pk_mul_f32 v[108:109], v[104:105], v[122:123] op_sel_hi:[1,0]
	v_pk_mul_f32 v[106:107], v[106:107], v[122:123] op_sel_hi:[1,0]
	s_cbranch_vccnz .LBB0_700
	s_cmpk_gt_u32 s94, 0x87f
	s_cbranch_scc1 .LBB0_699
	s_cmpk_lt_u32 s94, 0x580
	s_cbranch_scc1 .LBB0_691
	s_cmpk_lt_u32 s94, 0x680
	s_cbranch_scc1 .LBB0_688
	v_readlane_b32 s6, v248, 12
	v_readlane_b32 s7, v248, 13
	s_add_i32 s48, s94, 0xfffff980
	s_nop 0
	v_lshl_add_u64 v[104:105], s[6:7], 0, v[112:113]
	v_readlane_b32 s6, v248, 16
	v_readlane_b32 s7, v248, 17
	v_lshl_add_u64 v[126:127], s[48:49], 1, v[104:105]
	s_lshr_b32 s48, s48, 3
	v_lshl_add_u64 v[104:105], s[6:7], 0, v[120:121]
	v_lshl_add_u64 v[104:105], v[104:105], 0, s[48:49]
	s_lshl_b32 s48, s97, 2
	v_lshl_add_u64 v[104:105], v[104:105], 0, s[48:49]
	s_mov_b64 s[6:7], 0

;     DI void operator()(const f32x4 (&acc)[2][2][4][2], const Unit& u, int wr, int wc, int fr, int fq) const {
;     ...
;             for (int m = 0; m < 4; ++m) {
;                 const int row = row0 + ai * 128 + m * 16; const float rs = row_rstd<16>(P, row, 1.0f / 1024.0f);
; #pragma unroll
;                 for (int bj = 0; bj < 2; ++bj) {
;                     const int c128 = u.pn * 256 + bj * 128;
;                     float v[8];
; #pragma unroll
;                     for (int n = 0; n < 2; ++n)
; #pragma unroll
;                         for (int i = 0; i < 4; ++i) v[4 * n + i] = acc[ai][bj][m][n][i] * rs;
;                     if (c128 < 1024) {
.LBB0_731:
	s_waitcnt lgkmcnt(0)
	v_or_b32_e32 v98, 32, v154
	v_ashrrev_i32_e32 v99, 31, v98
	v_lshl_add_u64 v[96:97], v[98:99], 2, s[52:53]
	s_nop 0
	v_mad_i64_i32 v[100:101], s[10:11], v98, s33, 0
	s_and_b64 vcc, exec, s[8:9]
	v_lshlrev_b64 v[104:105], 6, v[98:99]
	v_lshlrev_b64 v[102:103], 9, v[98:99]
	s_mov_b64 s[10:11], -1
	s_waitcnt lgkmcnt(0)
	v_fmamk_f32 v96, v238, 0x3a800000, v174
	v_rsq_f32_e32 v106, v96
	v_lshlrev_b64 v[96:97], 10, v[98:99]
	v_pk_mul_f32 v[108:109], v[92:93], v[106:107] op_sel_hi:[1,0]
	v_pk_mul_f32 v[94:95], v[94:95], v[106:107] op_sel_hi:[1,0]
	v_pk_mul_f32 v[92:93], v[88:89], v[106:107] op_sel_hi:[1,0]
	v_pk_mul_f32 v[90:91], v[90:91], v[106:107] op_sel_hi:[1,0]
	s_cbranch_vccnz .LBB0_748
	s_cmpk_gt_u32 s94, 0x87f
	s_cbranch_scc1 .LBB0_747
	s_cmpk_lt_u32 s94, 0x580
	s_cbranch_scc1 .LBB0_739
	s_cmpk_lt_u32 s94, 0x680
	s_cbranch_scc1 .LBB0_736
	v_readlane_b32 s10, v248, 12
	v_readlane_b32 s11, v248, 13
	s_add_i32 s48, s94, 0xfffff980
	s_nop 0
	v_lshl_add_u64 v[88:89], s[10:11], 0, v[96:97]
	v_readlane_b32 s10, v248, 16
	v_readlane_b32 s11, v248, 17
	v_lshl_add_u64 v[110:111], s[48:49], 1, v[88:89]
	s_lshr_b32 s48, s48, 3
	v_lshl_add_u64 v[88:89], s[10:11], 0, v[104:105]
	v_lshl_add_u64 v[88:89], v[88:89], 0, s[48:49]
	s_lshl_b32 s48, s97, 2
	v_lshl_add_u64 v[88:89], v[88:89], 0, s[48:49]
	s_mov_b64 s[10:11], 0

;     DI void operator()(const f32x4 (&acc)[2][2][4][2], const Unit& u, int wr, int wc, int fr, int fq) const {
;     ...
;             for (int m = 0; m < 4; ++m) {
;                 const int row = row0 + ai * 128 + m * 16; const float rs = row_rstd<16>(P, row, 1.0f / 1024.0f);
; #pragma unroll
;                 for (int bj = 0; bj < 2; ++bj) {
;                     const int c128 = u.pn * 256 + bj * 128;
;                     float v[8];
; #pragma unroll
;                     for (int n = 0; n < 2; ++n)
; #pragma unroll
;                         for (int i = 0; i < 4; ++i) v[4 * n + i] = acc[ai][bj][m][n][i] * rs;
;                     if (c128 < 1024) {
.LBB0_779:
	s_waitcnt lgkmcnt(0)
	v_or_b32_e32 v82, 48, v154
	v_ashrrev_i32_e32 v83, 31, v82
	v_lshl_add_u64 v[80:81], v[82:83], 2, s[52:53]
	s_nop 0
	v_mad_i64_i32 v[84:85], s[10:11], v82, s33, 0
	s_and_b64 vcc, exec, s[8:9]
	v_lshlrev_b64 v[88:89], 6, v[82:83]
	v_lshlrev_b64 v[86:87], 9, v[82:83]
	s_mov_b64 s[10:11], -1
	s_waitcnt lgkmcnt(0)
	v_fmamk_f32 v80, v239, 0x3a800000, v174
	v_rsq_f32_e32 v90, v80
	v_lshlrev_b64 v[80:81], 10, v[82:83]
	v_pk_mul_f32 v[92:93], v[76:77], v[90:91] op_sel_hi:[1,0]
	v_pk_mul_f32 v[78:79], v[78:79], v[90:91] op_sel_hi:[1,0]
	v_pk_mul_f32 v[76:77], v[72:73], v[90:91] op_sel_hi:[1,0]
	v_pk_mul_f32 v[74:75], v[74:75], v[90:91] op_sel_hi:[1,0]
	s_cbranch_vccnz .LBB0_796
	s_cmpk_gt_u32 s94, 0x87f
	s_cbranch_scc1 .LBB0_795
	s_cmpk_lt_u32 s94, 0x580
	s_cbranch_scc1 .LBB0_787
	s_cmpk_lt_u32 s94, 0x680
	s_cbranch_scc1 .LBB0_784
	v_readlane_b32 s10, v248, 12
	v_readlane_b32 s11, v248, 13
	s_add_i32 s48, s94, 0xfffff980
	s_nop 0
	v_lshl_add_u64 v[72:73], s[10:11], 0, v[80:81]
	v_readlane_b32 s10, v248, 16
	v_readlane_b32 s11, v248, 17
	v_lshl_add_u64 v[94:95], s[48:49], 1, v[72:73]
	s_lshr_b32 s48, s48, 3
	v_lshl_add_u64 v[72:73], s[10:11], 0, v[88:89]
	v_lshl_add_u64 v[72:73], v[72:73], 0, s[48:49]
	s_lshl_b32 s48, s97, 2
	v_lshl_add_u64 v[72:73], v[72:73], 0, s[48:49]
	s_mov_b64 s[10:11], 0

;     DI void operator()(const f32x4 (&acc)[2][2][4][2], const Unit& u, int wr, int wc, int fr, int fq) const {
;     ...
;             for (int m = 0; m < 4; ++m) {
;                 const int row = row0 + ai * 128 + m * 16; const float rs = row_rstd<16>(P, row, 1.0f / 1024.0f);
; #pragma unroll
;                 for (int bj = 0; bj < 2; ++bj) {
;                     const int c128 = u.pn * 256 + bj * 128;
;                     float v[8];
; #pragma unroll
;                     for (int n = 0; n < 2; ++n)
; #pragma unroll
;                         for (int i = 0; i < 4; ++i) v[4 * n + i] = acc[ai][bj][m][n][i] * rs;
;                     if (c128 < 1024) {
.LBB0_827:
	s_nop 0
	s_waitcnt lgkmcnt(0)
	v_add_u32_e32 v66, 0x80, v154
	v_ashrrev_i32_e32 v67, 31, v66
	v_mad_i64_i32 v[68:69], s[10:11], v66, s33, 0
	s_and_b64 vcc, exec, s[8:9]
	v_lshlrev_b64 v[72:73], 6, v[66:67]
	v_lshlrev_b64 v[70:71], 9, v[66:67]
	s_mov_b64 s[10:11], -1
	v_fmamk_f32 v64, v240, 0x3a800000, v174
	v_rsq_f32_e32 v74, v64
	v_lshlrev_b64 v[64:65], 10, v[66:67]
	v_pk_mul_f32 v[76:77], v[60:61], v[74:75] op_sel_hi:[1,0]
	v_pk_mul_f32 v[62:63], v[62:63], v[74:75] op_sel_hi:[1,0]
	v_pk_mul_f32 v[60:61], v[56:57], v[74:75] op_sel_hi:[1,0]
	v_pk_mul_f32 v[58:59], v[58:59], v[74:75] op_sel_hi:[1,0]
	s_cbranch_vccnz .LBB0_844
	s_cmpk_gt_u32 s94, 0x87f
	s_cbranch_scc1 .LBB0_843
	s_cmpk_lt_u32 s94, 0x580
	s_cbranch_scc1 .LBB0_835
	s_cmpk_lt_u32 s94, 0x680
	s_cbranch_scc1 .LBB0_832
	v_readlane_b32 s10, v248, 12
	v_readlane_b32 s11, v248, 13
	s_add_i32 s48, s94, 0xfffff980
	s_nop 0
	v_lshl_add_u64 v[56:57], s[10:11], 0, v[64:65]
	v_readlane_b32 s10, v248, 16
	v_readlane_b32 s11, v248, 17
	v_lshl_add_u64 v[78:79], s[48:49], 1, v[56:57]
	s_lshr_b32 s48, s48, 3
	v_lshl_add_u64 v[56:57], s[10:11], 0, v[72:73]
	v_lshl_add_u64 v[56:57], v[56:57], 0, s[48:49]
	s_lshl_b32 s48, s97, 2
	v_lshl_add_u64 v[56:57], v[56:57], 0, s[48:49]
	s_mov_b64 s[10:11], 0

;     DI void operator()(const f32x4 (&acc)[2][2][4][2], const Unit& u, int wr, int wc, int fr, int fq) const {
;     ...
;             for (int m = 0; m < 4; ++m) {
;                 const int row = row0 + ai * 128 + m * 16; const float rs = row_rstd<16>(P, row, 1.0f / 1024.0f);
; #pragma unroll
;                 for (int bj = 0; bj < 2; ++bj) {
;                     const int c128 = u.pn * 256 + bj * 128;
;                     float v[8];
; #pragma unroll
;                     for (int n = 0; n < 2; ++n)
; #pragma unroll
;                         for (int i = 0; i < 4; ++i) v[4 * n + i] = acc[ai][bj][m][n][i] * rs;
;                     if (c128 < 1024) {
.LBB0_875:
	s_nop 0
	s_waitcnt lgkmcnt(0)
	v_add_u32_e32 v50, 0x90, v154
	v_ashrrev_i32_e32 v51, 31, v50
	v_mad_i64_i32 v[52:53], s[10:11], v50, s33, 0
	s_and_b64 vcc, exec, s[8:9]
	v_lshlrev_b64 v[56:57], 6, v[50:51]
	v_lshlrev_b64 v[54:55], 9, v[50:51]
	s_mov_b64 s[10:11], -1
	v_fmamk_f32 v48, v241, 0x3a800000, v174
	v_rsq_f32_e32 v58, v48
	v_lshlrev_b64 v[48:49], 10, v[50:51]
	v_pk_mul_f32 v[60:61], v[44:45], v[58:59] op_sel_hi:[1,0]
	v_pk_mul_f32 v[46:47], v[46:47], v[58:59] op_sel_hi:[1,0]
	v_pk_mul_f32 v[44:45], v[40:41], v[58:59] op_sel_hi:[1,0]
	v_pk_mul_f32 v[42:43], v[42:43], v[58:59] op_sel_hi:[1,0]
	s_cbranch_vccnz .LBB0_892
	s_cmpk_gt_u32 s94, 0x87f
	s_cbranch_scc1 .LBB0_891
	s_cmpk_lt_u32 s94, 0x580
	s_cbranch_scc1 .LBB0_883
	s_cmpk_lt_u32 s94, 0x680
	s_cbranch_scc1 .LBB0_880
	v_readlane_b32 s10, v248, 12
	v_readlane_b32 s11, v248, 13
	s_add_i32 s48, s94, 0xfffff980
	s_nop 0
	v_lshl_add_u64 v[40:41], s[10:11], 0, v[48:49]
	v_readlane_b32 s10, v248, 16
	v_readlane_b32 s11, v248, 17
	v_lshl_add_u64 v[62:63], s[48:49], 1, v[40:41]
	s_lshr_b32 s48, s48, 3
	v_lshl_add_u64 v[40:41], s[10:11], 0, v[56:57]
	v_lshl_add_u64 v[40:41], v[40:41], 0, s[48:49]
	s_lshl_b32 s48, s97, 2
	v_lshl_add_u64 v[40:41], v[40:41], 0, s[48:49]
	s_mov_b64 s[10:11], 0

;     DI void operator()(const f32x4 (&acc)[2][2][4][2], const Unit& u, int wr, int wc, int fr, int fq) const {
;     ...
;             for (int m = 0; m < 4; ++m) {
;                 const int row = row0 + ai * 128 + m * 16; const float rs = row_rstd<16>(P, row, 1.0f / 1024.0f);
; #pragma unroll
;                 for (int bj = 0; bj < 2; ++bj) {
;                     const int c128 = u.pn * 256 + bj * 128;
;                     float v[8];
; #pragma unroll
;                     for (int n = 0; n < 2; ++n)
; #pragma unroll
;                         for (int i = 0; i < 4; ++i) v[4 * n + i] = acc[ai][bj][m][n][i] * rs;
;                     if (c128 < 1024) {
.LBB0_923:
	s_nop 0
	s_waitcnt lgkmcnt(0)
	v_add_u32_e32 v34, 0xa0, v154
	v_ashrrev_i32_e32 v35, 31, v34
	v_mad_i64_i32 v[36:37], s[10:11], v34, s33, 0
	s_and_b64 vcc, exec, s[8:9]
	v_lshlrev_b64 v[40:41], 6, v[34:35]
	v_lshlrev_b64 v[38:39], 9, v[34:35]
	s_mov_b64 s[10:11], -1
	v_fmamk_f32 v32, v242, 0x3a800000, v174
	v_rsq_f32_e32 v42, v32
	v_lshlrev_b64 v[32:33], 10, v[34:35]
	v_pk_mul_f32 v[44:45], v[28:29], v[42:43] op_sel_hi:[1,0]
	v_pk_mul_f32 v[30:31], v[30:31], v[42:43] op_sel_hi:[1,0]
	v_pk_mul_f32 v[28:29], v[24:25], v[42:43] op_sel_hi:[1,0]
	v_pk_mul_f32 v[26:27], v[26:27], v[42:43] op_sel_hi:[1,0]
	s_cbranch_vccnz .LBB0_940
	s_cmpk_gt_u32 s94, 0x87f
	s_cbranch_scc1 .LBB0_939
	s_cmpk_lt_u32 s94, 0x580
	s_cbranch_scc1 .LBB0_931
	s_cmpk_lt_u32 s94, 0x680
	s_cbranch_scc1 .LBB0_928
	v_readlane_b32 s10, v248, 12
	v_readlane_b32 s11, v248, 13
	s_add_i32 s48, s94, 0xfffff980
	s_nop 0
	v_lshl_add_u64 v[24:25], s[10:11], 0, v[32:33]
	v_readlane_b32 s10, v248, 16
	v_readlane_b32 s11, v248, 17
	v_lshl_add_u64 v[46:47], s[48:49], 1, v[24:25]
	s_lshr_b32 s48, s48, 3
	v_lshl_add_u64 v[24:25], s[10:11], 0, v[40:41]
	v_lshl_add_u64 v[24:25], v[24:25], 0, s[48:49]
	s_lshl_b32 s48, s97, 2
	v_lshl_add_u64 v[24:25], v[24:25], 0, s[48:49]
	s_mov_b64 s[10:11], 0

;     DI void operator()(const f32x4 (&acc)[2][2][4][2], const Unit& u, int wr, int wc, int fr, int fq) const {
;     ...
;             for (int m = 0; m < 4; ++m) {
;                 const int row = row0 + ai * 128 + m * 16; const float rs = row_rstd<16>(P, row, 1.0f / 1024.0f);
; #pragma unroll
;                 for (int bj = 0; bj < 2; ++bj) {
;                     const int c128 = u.pn * 256 + bj * 128;
;                     float v[8];
; #pragma unroll
;                     for (int n = 0; n < 2; ++n)
; #pragma unroll
;                         for (int i = 0; i < 4; ++i) v[4 * n + i] = acc[ai][bj][m][n][i] * rs;
;                     if (c128 < 1024) {
.LBB0_971:
	s_nop 0
	s_waitcnt lgkmcnt(0)
	v_add_u32_e32 v18, 0xb0, v154
	s_and_b64 vcc, exec, s[8:9]
	v_ashrrev_i32_e32 v19, 31, v18
	v_mad_i64_i32 v[20:21], s[8:9], v18, s33, 0
	v_lshlrev_b64 v[24:25], 6, v[18:19]
	v_lshlrev_b64 v[22:23], 9, v[18:19]
	s_mov_b64 s[8:9], -1
	v_fmamk_f32 v16, v243, 0x3a800000, v174
	v_rsq_f32_e32 v26, v16
	v_lshlrev_b64 v[16:17], 10, v[18:19]
	v_pk_mul_f32 v[28:29], v[12:13], v[26:27] op_sel_hi:[1,0]
	v_pk_mul_f32 v[14:15], v[14:15], v[26:27] op_sel_hi:[1,0]
	v_pk_mul_f32 v[12:13], v[8:9], v[26:27] op_sel_hi:[1,0]
	v_pk_mul_f32 v[10:11], v[10:11], v[26:27] op_sel_hi:[1,0]
	s_cbranch_vccnz .LBB0_988
	s_cmpk_gt_u32 s94, 0x87f
	s_cbranch_scc1 .LBB0_987
	s_cmpk_lt_u32 s94, 0x580
	s_cbranch_scc1 .LBB0_979
	s_cmpk_lt_u32 s94, 0x680
	s_cbranch_scc1 .LBB0_976
	v_readlane_b32 s8, v248, 12
	v_readlane_b32 s9, v248, 13
	s_add_i32 s48, s94, 0xfffff980
	s_nop 0
	v_lshl_add_u64 v[8:9], s[8:9], 0, v[16:17]
	v_readlane_b32 s8, v248, 16
	v_readlane_b32 s9, v248, 17
	v_lshl_add_u64 v[30:31], s[48:49], 1, v[8:9]
	s_lshr_b32 s48, s48, 3
	v_lshl_add_u64 v[8:9], s[8:9], 0, v[24:25]
	v_lshl_add_u64 v[8:9], v[8:9], 0, s[48:49]
	s_lshl_b32 s48, s97, 2
	v_lshl_add_u64 v[8:9], v[8:9], 0, s[48:49]
	s_mov_b64 s[8:9], 0

; DI unsigned pk2(float lo, float hi) { typedef float v2f __attribute__((ext_vector_type(2))); typedef __bf16 v2b __attribute__((ext_vector_type(2))); v2f v = {lo, hi}; v2b b = __builtin_convertvector(v, v2b); return __builtin_bit_cast(unsigned, b); }
; DI float sigmoidf_(float v) { return __builtin_amdgcn_rcpf(1.0f + __expf(-v)); }
;     DI void operator()(const f32x4 (&acc)[2][2][4][2], const Unit& u, int wr, int wc, int fr, int fq) const {
;         const int row0 = u.pm * 256 + wr * 64 + fr, br = u.pn >> 2, cw = (u.pn & 3) * 256 + wc * 32 + 8 * fq;
;         bf16_t* G = G0 + (size_t)br * (16u << 20);
;         f32x4 bv[2][2];
; #pragma unroll
;         for (int bj = 0; bj < 2; ++bj)
; #pragma unroll
;             for (int n = 0; n < 2; ++n) bv[bj][n] = *(const f32x4*)(bias + br * 1024 + cw + bj * 128 + 4 * n);
; #pragma unroll
;         for (int ai = 0; ai < 2; ++ai)
; #pragma unroll
;             for (int m = 0; m < 4; ++m) {
;                 const int row = row0 + ai * 128 + m * 16; const float rs = row_rstd<16>(P, row, 1.0f / 1024.0f);
; #pragma unroll
;                 for (int bj = 0; bj < 2; ++bj) {
;                     float v[8];
; #pragma unroll
;                     for (int n = 0; n < 2; ++n)
; #pragma unroll
;                         for (int i = 0; i < 4; ++i) v[4 * n + i] = sigmoidf_(acc[ai][bj][m][n][i] * rs + bv[bj][n][i]);
;                     u32x4 w; w.x = pk2(v[0], v[1]); w.y = pk2(v[2], v[3]); w.z = pk2(v[4], v[5]); w.w = pk2(v[6], v[7]);
;                     *(u32x4*)(G + (size_t)row * DM + cw + bj * 128) = w;
;                 }
.LBB0_1602:
	s_lshl_b32 s13, s61, 8
	v_lshl_add_u32 v166, s34, 8, v170
	s_ashr_i32 s12, s61, 2
	s_and_b32 s13, s13, 0x300
	v_ashrrev_i32_e32 v167, 31, v166
	v_or_b32_e32 v152, s13, v172
	s_ashr_i32 s13, s12, 31
	v_lshl_add_u64 v[164:165], v[166:167], 2, s[6:7]
	s_lshl_b64 s[38:39], s[12:13], 25
	s_lshl_b32 s12, s12, 10
	global_load_dword v230, v[164:165], off
	global_load_dword v231, v[164:165], off offset:64
	global_load_dword v232, v[164:165], off offset:128
	global_load_dword v233, v[164:165], off offset:192
	global_load_dword v234, v[164:165], off offset:512
	global_load_dword v235, v[164:165], off offset:576
	global_load_dword v236, v[164:165], off offset:640
	global_load_dword v237, v[164:165], off offset:704
	s_ashr_i32 s13, s12, 31
	s_lshl_b64 s[12:13], s[12:13], 2
	v_readlane_b32 s40, v249, 33
	v_readlane_b32 s41, v249, 34
	s_add_u32 s12, s40, s12
	s_addc_u32 s13, s41, s13
	v_lshlrev_b32_e32 v72, 2, v152
	global_load_dwordx4 v[92:95], v72, s[12:13]
	global_load_dwordx4 v[88:91], v72, s[12:13] offset:16
	global_load_dwordx4 v[84:87], v72, s[12:13] offset:512
	s_nop 0
	global_load_dwordx4 v[72:75], v72, s[12:13] offset:528
	v_lshlrev_b64 v[162:163], 11, v[166:167]
	s_add_u32 s12, s80, s38
	v_lshlrev_b32_e32 v152, 1, v152
	s_addc_u32 s13, s81, s39
	v_readlane_b32 s42, v249, 35
	v_readlane_b32 s43, v249, 36
	v_readlane_b32 s44, v249, 37
	v_readlane_b32 s45, v249, 38
	v_readlane_b32 s46, v249, 39
	v_readlane_b32 s47, v249, 40
	v_readlane_b32 s48, v249, 41
	v_readlane_b32 s49, v249, 42
	v_readlane_b32 s50, v249, 43
	v_readlane_b32 s51, v249, 44
	v_readlane_b32 s52, v249, 45
	v_readlane_b32 s53, v249, 46
	v_readlane_b32 s54, v249, 47
	v_readlane_b32 s55, v249, 48
	s_waitcnt vmcnt(0) lgkmcnt(0)
	v_fmamk_f32 v167, v230, 0x3a800000, v176
	v_rsq_f32_e32 v167, v167
	v_lshl_add_u64 v[168:169], s[12:13], 0, v[152:153]
	v_lshl_add_u64 v[162:163], v[168:169], 0, v[162:163]
	v_fma_f32 v140, v140, v167, v92
	v_fma_f32 v141, v141, v167, v93
	v_fma_f32 v142, v142, v167, v94
	v_fma_f32 v128, v128, v167, v72
	v_fma_f32 v129, v129, v167, v73
	v_mul_f32_e32 v128, 0xbfb8aa3b, v128
	v_fma_f32 v143, v143, v167, v95
	v_fma_f32 v136, v136, v167, v88
	v_fma_f32 v137, v137, v167, v89
	v_fma_f32 v138, v138, v167, v90
	v_fma_f32 v139, v139, v167, v91
	v_mul_f32_e32 v129, 0xbfb8aa3b, v129
	v_exp_f32_e32 v128, v128
	v_mul_f32_e32 v140, 0xbfb8aa3b, v140
	v_mul_f32_e32 v141, 0xbfb8aa3b, v141
	v_mul_f32_e32 v142, 0xbfb8aa3b, v142
	v_mul_f32_e32 v143, 0xbfb8aa3b, v143
	v_mul_f32_e32 v136, 0xbfb8aa3b, v136
	v_mul_f32_e32 v137, 0xbfb8aa3b, v137
	v_mul_f32_e32 v138, 0xbfb8aa3b, v138
	v_mul_f32_e32 v139, 0xbfb8aa3b, v139
	v_exp_f32_e32 v129, v129
	v_exp_f32_e32 v140, v140
	v_exp_f32_e32 v141, v141
	v_exp_f32_e32 v142, v142
	v_exp_f32_e32 v143, v143
	v_exp_f32_e32 v136, v136
	v_exp_f32_e32 v137, v137
	v_exp_f32_e32 v138, v138
	v_exp_f32_e32 v139, v139
	v_fma_f32 v132, v132, v167, v84
	v_fma_f32 v133, v133, v167, v85
	v_fma_f32 v134, v134, v167, v86
	v_fma_f32 v135, v135, v167, v87
	v_add_f32_e32 v128, 1.0, v128
	v_mul_f32_e32 v132, 0xbfb8aa3b, v132
	v_mul_f32_e32 v133, 0xbfb8aa3b, v133
	v_mul_f32_e32 v134, 0xbfb8aa3b, v134
	v_mul_f32_e32 v135, 0xbfb8aa3b, v135
	v_rcp_f32_e32 v180, v128
	v_add_f32_e32 v128, 1.0, v129
	v_fma_f32 v129, v130, v167, v74
	v_exp_f32_e32 v132, v132
	v_exp_f32_e32 v133, v133
	v_exp_f32_e32 v134, v134
	v_exp_f32_e32 v135, v135
	v_add_f32_e32 v140, 1.0, v140
	v_add_f32_e32 v141, 1.0, v141
	v_add_f32_e32 v142, 1.0, v142
	v_add_f32_e32 v143, 1.0, v143
	v_add_f32_e32 v136, 1.0, v136
	v_add_f32_e32 v137, 1.0, v137
	v_add_f32_e32 v138, 1.0, v138
	v_add_f32_e32 v139, 1.0, v139
	v_mul_f32_e32 v129, 0xbfb8aa3b, v129
	v_fma_f32 v130, v131, v167, v75
	v_rcp_f32_e32 v140, v140
	v_rcp_f32_e32 v141, v141
	v_rcp_f32_e32 v142, v142
	v_rcp_f32_e32 v143, v143
	v_rcp_f32_e32 v136, v136
	v_rcp_f32_e32 v137, v137
	v_rcp_f32_e32 v138, v138
	v_rcp_f32_e32 v139, v139
	v_exp_f32_e32 v129, v129
	v_mul_f32_e32 v130, 0xbfb8aa3b, v130
	v_exp_f32_e32 v130, v130
	v_add_f32_e32 v132, 1.0, v132
	v_add_f32_e32 v133, 1.0, v133
	v_add_f32_e32 v134, 1.0, v134
	v_add_f32_e32 v135, 1.0, v135
	v_rcp_f32_e32 v152, v132
	v_rcp_f32_e32 v177, v133
	v_rcp_f32_e32 v178, v134
	v_rcp_f32_e32 v179, v135
	v_cvt_pk_bf16_f32 v132, v140, v141
	v_cvt_pk_bf16_f32 v133, v142, v143
	v_cvt_pk_bf16_f32 v134, v136, v137
	v_cvt_pk_bf16_f32 v135, v138, v139
	v_rcp_f32_e32 v131, v128
	v_add_f32_e32 v128, 1.0, v129
	flat_store_dwordx4 v[162:163], v[132:135]
	v_cvt_pk_bf16_f32 v129, v178, v179
	s_nop 0
	v_rcp_f32_e32 v132, v128
	v_add_f32_e32 v128, 1.0, v130
	v_rcp_f32_e32 v133, v128
	v_cvt_pk_bf16_f32 v128, v152, v177
	v_cvt_pk_bf16_f32 v130, v180, v131
	v_cvt_pk_bf16_f32 v131, v132, v133
	flat_store_dwordx4 v[162:163], v[128:131] offset:256
	s_nop 1
	v_or_b32_e32 v128, 16, v166
	v_ashrrev_i32_e32 v129, 31, v128
	v_lshl_add_u64 v[130:131], v[128:129], 2, s[6:7]
	s_nop 0
	v_lshlrev_b64 v[128:129], 11, v[128:129]
	v_lshl_add_u64 v[128:129], v[168:169], 0, v[128:129]
	v_fmamk_f32 v130, v231, 0x3a800000, v176
	v_rsq_f32_e32 v130, v130
	s_nop 0
	v_fma_f32 v112, v112, v130, v72
	v_fma_f32 v113, v113, v130, v73
	v_mul_f32_e32 v112, 0xbfb8aa3b, v112
	v_fma_f32 v124, v124, v130, v92
	v_fma_f32 v125, v125, v130, v93
	v_fma_f32 v126, v126, v130, v94
	v_fma_f32 v127, v127, v130, v95
	v_fma_f32 v120, v120, v130, v88
	v_fma_f32 v121, v121, v130, v89
	v_fma_f32 v122, v122, v130, v90
	v_fma_f32 v123, v123, v130, v91
	v_mul_f32_e32 v113, 0xbfb8aa3b, v113
	v_exp_f32_e32 v112, v112
	v_mul_f32_e32 v124, 0xbfb8aa3b, v124
	v_mul_f32_e32 v125, 0xbfb8aa3b, v125
	v_mul_f32_e32 v126, 0xbfb8aa3b, v126
	v_mul_f32_e32 v127, 0xbfb8aa3b, v127
; DI unsigned pk2(float lo, float hi) { typedef float v2f __attribute__((ext_vector_type(2))); typedef __bf16 v2b __attribute__((ext_vector_type(2))); v2f v = {lo, hi}; v2b b = __builtin_convertvector(v, v2b); return __builtin_bit_cast(unsigned, b); }
; DI float sigmoidf_(float v) { return __builtin_amdgcn_rcpf(1.0f + __expf(-v)); }
;     DI void operator()(const f32x4 (&acc)[2][2][4][2], const Unit& u, int wr, int wc, int fr, int fq) const {
;     ...
;                 const int row = row0 + ai * 128 + m * 16; const float rs = row_rstd<16>(P, row, 1.0f / 1024.0f);
; #pragma unroll
;                 for (int bj = 0; bj < 2; ++bj) {
;                     float v[8];
; #pragma unroll
;                     for (int n = 0; n < 2; ++n)
; #pragma unroll
;                         for (int i = 0; i < 4; ++i) v[4 * n + i] = sigmoidf_(acc[ai][bj][m][n][i] * rs + bv[bj][n][i]);
;                     u32x4 w; w.x = pk2(v[0], v[1]); w.y = pk2(v[2], v[3]); w.z = pk2(v[4], v[5]); w.w = pk2(v[6], v[7]);
;                     *(u32x4*)(G + (size_t)row * DM + cw + bj * 128) = w;
;                 }
	v_mul_f32_e32 v120, 0xbfb8aa3b, v120
	v_mul_f32_e32 v121, 0xbfb8aa3b, v121
	v_mul_f32_e32 v122, 0xbfb8aa3b, v122
	v_mul_f32_e32 v123, 0xbfb8aa3b, v123
	v_exp_f32_e32 v113, v113
	v_exp_f32_e32 v124, v124
	v_exp_f32_e32 v125, v125
	v_exp_f32_e32 v126, v126
	v_exp_f32_e32 v127, v127
	v_exp_f32_e32 v120, v120
	v_exp_f32_e32 v121, v121
	v_exp_f32_e32 v122, v122
	v_exp_f32_e32 v123, v123
	v_fma_f32 v116, v116, v130, v84
	v_fma_f32 v117, v117, v130, v85
	v_fma_f32 v118, v118, v130, v86
	v_fma_f32 v119, v119, v130, v87
	v_add_f32_e32 v112, 1.0, v112
	v_mul_f32_e32 v116, 0xbfb8aa3b, v116
	v_mul_f32_e32 v117, 0xbfb8aa3b, v117
	v_mul_f32_e32 v118, 0xbfb8aa3b, v118
	v_mul_f32_e32 v119, 0xbfb8aa3b, v119
	v_rcp_f32_e32 v135, v112
	v_add_f32_e32 v112, 1.0, v113
	v_fma_f32 v113, v114, v130, v74
	v_exp_f32_e32 v116, v116
	v_exp_f32_e32 v117, v117
	v_exp_f32_e32 v118, v118
	v_exp_f32_e32 v119, v119
	v_add_f32_e32 v124, 1.0, v124
	v_add_f32_e32 v125, 1.0, v125
	v_add_f32_e32 v126, 1.0, v126
	v_add_f32_e32 v127, 1.0, v127
	v_add_f32_e32 v120, 1.0, v120
	v_add_f32_e32 v121, 1.0, v121
	v_add_f32_e32 v122, 1.0, v122
	v_add_f32_e32 v123, 1.0, v123
	v_mul_f32_e32 v113, 0xbfb8aa3b, v113
	v_fma_f32 v114, v115, v130, v75
	v_rcp_f32_e32 v124, v124
	v_rcp_f32_e32 v125, v125
	v_rcp_f32_e32 v126, v126
	v_rcp_f32_e32 v127, v127
	v_rcp_f32_e32 v120, v120
	v_rcp_f32_e32 v121, v121
	v_rcp_f32_e32 v122, v122
	v_rcp_f32_e32 v123, v123
	v_exp_f32_e32 v113, v113
	v_mul_f32_e32 v114, 0xbfb8aa3b, v114
	v_exp_f32_e32 v114, v114
	v_add_f32_e32 v116, 1.0, v116
	v_add_f32_e32 v117, 1.0, v117
	v_add_f32_e32 v118, 1.0, v118
	v_add_f32_e32 v119, 1.0, v119
	v_rcp_f32_e32 v131, v116
	v_rcp_f32_e32 v132, v117
	v_rcp_f32_e32 v133, v118
	v_rcp_f32_e32 v134, v119
	v_cvt_pk_bf16_f32 v116, v124, v125
	v_cvt_pk_bf16_f32 v117, v126, v127
	v_cvt_pk_bf16_f32 v118, v120, v121
	v_cvt_pk_bf16_f32 v119, v122, v123
	v_rcp_f32_e32 v115, v112
	v_add_f32_e32 v112, 1.0, v113
	flat_store_dwordx4 v[128:129], v[116:119]
	v_cvt_pk_bf16_f32 v113, v133, v134
	s_nop 0
	v_rcp_f32_e32 v116, v112
	v_add_f32_e32 v112, 1.0, v114
	v_rcp_f32_e32 v117, v112
	v_cvt_pk_bf16_f32 v112, v131, v132
	v_cvt_pk_bf16_f32 v114, v135, v115
	v_cvt_pk_bf16_f32 v115, v116, v117
	flat_store_dwordx4 v[128:129], v[112:115] offset:256
	s_nop 1
	v_or_b32_e32 v112, 32, v166
	v_ashrrev_i32_e32 v113, 31, v112
	v_lshl_add_u64 v[114:115], v[112:113], 2, s[6:7]
	s_nop 0
	v_lshlrev_b64 v[112:113], 11, v[112:113]
	v_lshl_add_u64 v[112:113], v[168:169], 0, v[112:113]
	v_fmamk_f32 v114, v232, 0x3a800000, v176
	v_rsq_f32_e32 v114, v114
	s_nop 0
	v_fma_f32 v96, v96, v114, v72
	v_fma_f32 v97, v97, v114, v73
	v_mul_f32_e32 v96, 0xbfb8aa3b, v96
	v_fma_f32 v108, v108, v114, v92
	v_fma_f32 v109, v109, v114, v93
	v_fma_f32 v110, v110, v114, v94
	v_fma_f32 v111, v111, v114, v95
	v_fma_f32 v104, v104, v114, v88
	v_fma_f32 v105, v105, v114, v89
	v_fma_f32 v106, v106, v114, v90
	v_fma_f32 v107, v107, v114, v91
	v_mul_f32_e32 v97, 0xbfb8aa3b, v97
	v_exp_f32_e32 v96, v96
	v_mul_f32_e32 v108, 0xbfb8aa3b, v108
	v_mul_f32_e32 v109, 0xbfb8aa3b, v109
	v_mul_f32_e32 v110, 0xbfb8aa3b, v110
	v_mul_f32_e32 v111, 0xbfb8aa3b, v111
	v_mul_f32_e32 v104, 0xbfb8aa3b, v104
	v_mul_f32_e32 v105, 0xbfb8aa3b, v105
	v_mul_f32_e32 v106, 0xbfb8aa3b, v106
	v_mul_f32_e32 v107, 0xbfb8aa3b, v107
	v_exp_f32_e32 v97, v97
	v_exp_f32_e32 v108, v108
	v_exp_f32_e32 v109, v109
	v_exp_f32_e32 v110, v110
	v_exp_f32_e32 v111, v111
	v_exp_f32_e32 v104, v104
	v_exp_f32_e32 v105, v105
	v_exp_f32_e32 v106, v106
	v_exp_f32_e32 v107, v107
	v_fma_f32 v100, v100, v114, v84
	v_fma_f32 v101, v101, v114, v85
	v_fma_f32 v102, v102, v114, v86
	v_fma_f32 v103, v103, v114, v87
	v_add_f32_e32 v96, 1.0, v96
	v_mul_f32_e32 v100, 0xbfb8aa3b, v100
	v_mul_f32_e32 v101, 0xbfb8aa3b, v101
	v_mul_f32_e32 v102, 0xbfb8aa3b, v102
	v_mul_f32_e32 v103, 0xbfb8aa3b, v103
	v_rcp_f32_e32 v119, v96
	v_add_f32_e32 v96, 1.0, v97
	v_fma_f32 v97, v98, v114, v74
	v_exp_f32_e32 v100, v100
	v_exp_f32_e32 v101, v101
	v_exp_f32_e32 v102, v102
	v_exp_f32_e32 v103, v103
	v_add_f32_e32 v108, 1.0, v108
	v_add_f32_e32 v109, 1.0, v109
	v_add_f32_e32 v110, 1.0, v110
	v_add_f32_e32 v111, 1.0, v111
	v_add_f32_e32 v104, 1.0, v104
	v_add_f32_e32 v105, 1.0, v105
	v_add_f32_e32 v106, 1.0, v106
	v_add_f32_e32 v107, 1.0, v107
	v_mul_f32_e32 v97, 0xbfb8aa3b, v97
	v_fma_f32 v98, v99, v114, v75
	v_rcp_f32_e32 v108, v108
	v_rcp_f32_e32 v109, v109
	v_rcp_f32_e32 v110, v110
	v_rcp_f32_e32 v111, v111
	v_rcp_f32_e32 v104, v104
	v_rcp_f32_e32 v105, v105
	v_rcp_f32_e32 v106, v106
	v_rcp_f32_e32 v107, v107
	v_exp_f32_e32 v97, v97
	v_mul_f32_e32 v98, 0xbfb8aa3b, v98
	v_exp_f32_e32 v98, v98
	v_add_f32_e32 v100, 1.0, v100
	v_add_f32_e32 v101, 1.0, v101
	v_add_f32_e32 v102, 1.0, v102
	v_add_f32_e32 v103, 1.0, v103
	v_rcp_f32_e32 v115, v100
	v_rcp_f32_e32 v116, v101
	v_rcp_f32_e32 v117, v102
	v_rcp_f32_e32 v118, v103
	v_cvt_pk_bf16_f32 v100, v108, v109
	v_cvt_pk_bf16_f32 v101, v110, v111
	v_cvt_pk_bf16_f32 v102, v104, v105
	v_cvt_pk_bf16_f32 v103, v106, v107
	v_rcp_f32_e32 v99, v96
	v_add_f32_e32 v96, 1.0, v97
	flat_store_dwordx4 v[112:113], v[100:103]
	v_cvt_pk_bf16_f32 v97, v117, v118
	s_nop 0
	v_rcp_f32_e32 v100, v96
	v_add_f32_e32 v96, 1.0, v98
	v_rcp_f32_e32 v101, v96
	v_cvt_pk_bf16_f32 v96, v115, v116
	v_cvt_pk_bf16_f32 v98, v119, v99
	v_cvt_pk_bf16_f32 v99, v100, v101
	flat_store_dwordx4 v[112:113], v[96:99] offset:256
	s_nop 1
	v_or_b32_e32 v96, 48, v166
	v_ashrrev_i32_e32 v97, 31, v96
	v_lshl_add_u64 v[98:99], v[96:97], 2, s[6:7]
	s_nop 0
	v_lshlrev_b64 v[96:97], 11, v[96:97]
	v_lshl_add_u64 v[96:97], v[168:169], 0, v[96:97]
	v_fmamk_f32 v98, v233, 0x3a800000, v176
; DI unsigned pk2(float lo, float hi) { typedef float v2f __attribute__((ext_vector_type(2))); typedef __bf16 v2b __attribute__((ext_vector_type(2))); v2f v = {lo, hi}; v2b b = __builtin_convertvector(v, v2b); return __builtin_bit_cast(unsigned, b); }
; DI float sigmoidf_(float v) { return __builtin_amdgcn_rcpf(1.0f + __expf(-v)); }
;     DI void operator()(const f32x4 (&acc)[2][2][4][2], const Unit& u, int wr, int wc, int fr, int fq) const {
;     ...
;                 const int row = row0 + ai * 128 + m * 16; const float rs = row_rstd<16>(P, row, 1.0f / 1024.0f);
; #pragma unroll
;                 for (int bj = 0; bj < 2; ++bj) {
;                     float v[8];
; #pragma unroll
;                     for (int n = 0; n < 2; ++n)
; #pragma unroll
;                         for (int i = 0; i < 4; ++i) v[4 * n + i] = sigmoidf_(acc[ai][bj][m][n][i] * rs + bv[bj][n][i]);
;                     u32x4 w; w.x = pk2(v[0], v[1]); w.y = pk2(v[2], v[3]); w.z = pk2(v[4], v[5]); w.w = pk2(v[6], v[7]);
;                     *(u32x4*)(G + (size_t)row * DM + cw + bj * 128) = w;
;                 }
	v_rsq_f32_e32 v98, v98
	s_nop 0
	v_fma_f32 v64, v64, v98, v72
	v_fma_f32 v65, v65, v98, v73
	v_mul_f32_e32 v64, 0xbfb8aa3b, v64
	v_fma_f32 v80, v80, v98, v92
	v_fma_f32 v81, v81, v98, v93
	v_fma_f32 v82, v82, v98, v94
	v_fma_f32 v83, v83, v98, v95
	v_fma_f32 v76, v76, v98, v88
	v_fma_f32 v77, v77, v98, v89
	v_fma_f32 v78, v78, v98, v90
	v_fma_f32 v79, v79, v98, v91
	v_mul_f32_e32 v65, 0xbfb8aa3b, v65
	v_exp_f32_e32 v64, v64
	v_mul_f32_e32 v80, 0xbfb8aa3b, v80
	v_mul_f32_e32 v81, 0xbfb8aa3b, v81
	v_mul_f32_e32 v82, 0xbfb8aa3b, v82
	v_mul_f32_e32 v83, 0xbfb8aa3b, v83
	v_mul_f32_e32 v76, 0xbfb8aa3b, v76
	v_mul_f32_e32 v77, 0xbfb8aa3b, v77
	v_mul_f32_e32 v78, 0xbfb8aa3b, v78
	v_mul_f32_e32 v79, 0xbfb8aa3b, v79
	v_exp_f32_e32 v65, v65
	v_exp_f32_e32 v80, v80
	v_exp_f32_e32 v81, v81
	v_exp_f32_e32 v82, v82
	v_exp_f32_e32 v83, v83
	v_exp_f32_e32 v76, v76
	v_exp_f32_e32 v77, v77
	v_exp_f32_e32 v78, v78
	v_exp_f32_e32 v79, v79
	v_fma_f32 v68, v68, v98, v84
	v_fma_f32 v69, v69, v98, v85
	v_fma_f32 v70, v70, v98, v86
	v_fma_f32 v71, v71, v98, v87
	v_add_f32_e32 v64, 1.0, v64
	v_mul_f32_e32 v68, 0xbfb8aa3b, v68
	v_mul_f32_e32 v69, 0xbfb8aa3b, v69
	v_mul_f32_e32 v70, 0xbfb8aa3b, v70
	v_mul_f32_e32 v71, 0xbfb8aa3b, v71
	v_rcp_f32_e32 v103, v64
	v_add_f32_e32 v64, 1.0, v65
	v_fma_f32 v65, v66, v98, v74
	v_exp_f32_e32 v68, v68
	v_exp_f32_e32 v69, v69
	v_exp_f32_e32 v70, v70
	v_exp_f32_e32 v71, v71
	v_add_f32_e32 v80, 1.0, v80
	v_add_f32_e32 v81, 1.0, v81
	v_add_f32_e32 v82, 1.0, v82
	v_add_f32_e32 v83, 1.0, v83
	v_add_f32_e32 v76, 1.0, v76
	v_add_f32_e32 v77, 1.0, v77
	v_add_f32_e32 v78, 1.0, v78
	v_add_f32_e32 v79, 1.0, v79
	v_mul_f32_e32 v65, 0xbfb8aa3b, v65
	v_fma_f32 v66, v67, v98, v75
	v_rcp_f32_e32 v80, v80
	v_rcp_f32_e32 v81, v81
	v_rcp_f32_e32 v82, v82
	v_rcp_f32_e32 v83, v83
	v_rcp_f32_e32 v76, v76
	v_rcp_f32_e32 v77, v77
	v_rcp_f32_e32 v78, v78
	v_rcp_f32_e32 v79, v79
	v_exp_f32_e32 v65, v65
	v_mul_f32_e32 v66, 0xbfb8aa3b, v66
	v_exp_f32_e32 v66, v66
	v_add_f32_e32 v68, 1.0, v68
	v_add_f32_e32 v69, 1.0, v69
	v_add_f32_e32 v70, 1.0, v70
	v_add_f32_e32 v71, 1.0, v71
	v_rcp_f32_e32 v99, v68
	v_rcp_f32_e32 v100, v69
	v_rcp_f32_e32 v101, v70
	v_rcp_f32_e32 v102, v71
	v_cvt_pk_bf16_f32 v68, v80, v81
	v_cvt_pk_bf16_f32 v69, v82, v83
	v_cvt_pk_bf16_f32 v70, v76, v77
	v_cvt_pk_bf16_f32 v71, v78, v79
	v_rcp_f32_e32 v67, v64
	v_add_f32_e32 v64, 1.0, v65
	flat_store_dwordx4 v[96:97], v[68:71]
	v_cvt_pk_bf16_f32 v65, v101, v102
	s_nop 0
	v_rcp_f32_e32 v68, v64
	v_add_f32_e32 v64, 1.0, v66
	v_rcp_f32_e32 v69, v64
	v_cvt_pk_bf16_f32 v64, v99, v100
	v_cvt_pk_bf16_f32 v66, v103, v67
	v_cvt_pk_bf16_f32 v67, v68, v69
	flat_store_dwordx4 v[96:97], v[64:67] offset:256
	s_nop 0
	s_nop 0
	v_lshl_add_u64 v[64:65], v[162:163], 0, s[0:1]
	v_fmamk_f32 v66, v234, 0x3a800000, v176
	v_rsq_f32_e32 v68, v66
	v_add_co_u32_e32 v66, vcc, s57, v162
	v_fma_f32 v48, v48, v68, v72
	v_fma_f32 v49, v49, v68, v73
	v_mul_f32_e32 v48, 0xbfb8aa3b, v48
	v_fma_f32 v60, v60, v68, v92
	v_fma_f32 v61, v61, v68, v93
	v_fma_f32 v62, v62, v68, v94
	v_fma_f32 v63, v63, v68, v95
	v_fma_f32 v56, v56, v68, v88
	v_fma_f32 v57, v57, v68, v89
	v_fma_f32 v58, v58, v68, v90
	v_fma_f32 v59, v59, v68, v91
	v_mul_f32_e32 v49, 0xbfb8aa3b, v49
	v_exp_f32_e32 v48, v48
	v_mul_f32_e32 v60, 0xbfb8aa3b, v60
	v_mul_f32_e32 v61, 0xbfb8aa3b, v61
	v_mul_f32_e32 v62, 0xbfb8aa3b, v62
	v_mul_f32_e32 v63, 0xbfb8aa3b, v63
	v_mul_f32_e32 v56, 0xbfb8aa3b, v56
	v_mul_f32_e32 v57, 0xbfb8aa3b, v57
	v_mul_f32_e32 v58, 0xbfb8aa3b, v58
	v_mul_f32_e32 v59, 0xbfb8aa3b, v59
	v_exp_f32_e32 v49, v49
	v_exp_f32_e32 v60, v60
	v_exp_f32_e32 v61, v61
	v_exp_f32_e32 v62, v62
	v_exp_f32_e32 v63, v63
	v_exp_f32_e32 v56, v56
	v_exp_f32_e32 v57, v57
	v_exp_f32_e32 v58, v58
	v_exp_f32_e32 v59, v59
	v_fma_f32 v52, v52, v68, v84
	v_fma_f32 v53, v53, v68, v85
	v_fma_f32 v54, v54, v68, v86
	v_fma_f32 v55, v55, v68, v87
	v_add_f32_e32 v48, 1.0, v48
	v_mul_f32_e32 v52, 0xbfb8aa3b, v52
	v_mul_f32_e32 v53, 0xbfb8aa3b, v53
	v_mul_f32_e32 v54, 0xbfb8aa3b, v54
	v_mul_f32_e32 v55, 0xbfb8aa3b, v55
	v_rcp_f32_e32 v77, v48
	v_add_f32_e32 v48, 1.0, v49
	v_fma_f32 v49, v50, v68, v74
	v_exp_f32_e32 v52, v52
	v_exp_f32_e32 v53, v53
	v_exp_f32_e32 v54, v54
	v_exp_f32_e32 v55, v55
	v_add_f32_e32 v60, 1.0, v60
	v_add_f32_e32 v61, 1.0, v61
	v_add_f32_e32 v62, 1.0, v62
	v_add_f32_e32 v63, 1.0, v63
	v_add_f32_e32 v56, 1.0, v56
	v_add_f32_e32 v57, 1.0, v57
	v_add_f32_e32 v58, 1.0, v58
	v_add_f32_e32 v59, 1.0, v59
	v_mul_f32_e32 v49, 0xbfb8aa3b, v49
	v_fma_f32 v50, v51, v68, v75
	v_rcp_f32_e32 v60, v60
	v_rcp_f32_e32 v61, v61
	v_rcp_f32_e32 v62, v62
	v_rcp_f32_e32 v63, v63
	v_rcp_f32_e32 v56, v56
	v_rcp_f32_e32 v57, v57
	v_rcp_f32_e32 v58, v58
	v_rcp_f32_e32 v59, v59
	v_exp_f32_e32 v49, v49
	v_mul_f32_e32 v50, 0xbfb8aa3b, v50
	v_exp_f32_e32 v50, v50
	v_add_f32_e32 v52, 1.0, v52
	v_add_f32_e32 v53, 1.0, v53
	v_add_f32_e32 v54, 1.0, v54
	v_add_f32_e32 v55, 1.0, v55
	v_addc_co_u32_e32 v67, vcc, 0, v163, vcc
	v_rcp_f32_e32 v69, v52
	v_rcp_f32_e32 v70, v53
	v_rcp_f32_e32 v71, v54
	v_rcp_f32_e32 v76, v55
	v_cvt_pk_bf16_f32 v52, v60, v61
	v_cvt_pk_bf16_f32 v53, v62, v63
	v_cvt_pk_bf16_f32 v54, v56, v57
	v_cvt_pk_bf16_f32 v55, v58, v59
	v_rcp_f32_e32 v51, v48
	v_add_f32_e32 v48, 1.0, v49
	flat_store_dwordx4 v[66:67], v[52:55]
	v_cvt_pk_bf16_f32 v49, v71, v76
	s_nop 0
	v_rcp_f32_e32 v52, v48
	v_add_f32_e32 v48, 1.0, v50
	v_rcp_f32_e32 v53, v48
	v_cvt_pk_bf16_f32 v48, v69, v70
	v_cvt_pk_bf16_f32 v50, v77, v51
	v_cvt_pk_bf16_f32 v51, v52, v53
	flat_store_dwordx4 v[64:65], v[48:51] offset:256
	s_nop 0
	s_nop 0
	v_lshl_add_u64 v[48:49], v[162:163], 0, s[14:15]
; DI unsigned pk2(float lo, float hi) { typedef float v2f __attribute__((ext_vector_type(2))); typedef __bf16 v2b __attribute__((ext_vector_type(2))); v2f v = {lo, hi}; v2b b = __builtin_convertvector(v, v2b); return __builtin_bit_cast(unsigned, b); }
; DI float sigmoidf_(float v) { return __builtin_amdgcn_rcpf(1.0f + __expf(-v)); }
;     DI void operator()(const f32x4 (&acc)[2][2][4][2], const Unit& u, int wr, int wc, int fr, int fq) const {
;     ...
;                 const int row = row0 + ai * 128 + m * 16; const float rs = row_rstd<16>(P, row, 1.0f / 1024.0f);
; #pragma unroll
;                 for (int bj = 0; bj < 2; ++bj) {
;                     float v[8];
; #pragma unroll
;                     for (int n = 0; n < 2; ++n)
; #pragma unroll
;                         for (int i = 0; i < 4; ++i) v[4 * n + i] = sigmoidf_(acc[ai][bj][m][n][i] * rs + bv[bj][n][i]);
;                     u32x4 w; w.x = pk2(v[0], v[1]); w.y = pk2(v[2], v[3]); w.z = pk2(v[4], v[5]); w.w = pk2(v[6], v[7]);
;                     *(u32x4*)(G + (size_t)row * DM + cw + bj * 128) = w;
;                 }
	v_fmamk_f32 v50, v235, 0x3a800000, v176
	v_rsq_f32_e32 v52, v50
	v_add_co_u32_e32 v50, vcc, s58, v162
	v_fma_f32 v32, v32, v52, v72
	v_fma_f32 v33, v33, v52, v73
	v_mul_f32_e32 v32, 0xbfb8aa3b, v32
	v_fma_f32 v44, v44, v52, v92
	v_fma_f32 v45, v45, v52, v93
	v_fma_f32 v46, v46, v52, v94
	v_fma_f32 v47, v47, v52, v95
	v_fma_f32 v40, v40, v52, v88
	v_fma_f32 v41, v41, v52, v89
	v_fma_f32 v42, v42, v52, v90
	v_fma_f32 v43, v43, v52, v91
	v_mul_f32_e32 v33, 0xbfb8aa3b, v33
	v_exp_f32_e32 v32, v32
	v_mul_f32_e32 v44, 0xbfb8aa3b, v44
	v_mul_f32_e32 v45, 0xbfb8aa3b, v45
	v_mul_f32_e32 v46, 0xbfb8aa3b, v46
	v_mul_f32_e32 v47, 0xbfb8aa3b, v47
	v_mul_f32_e32 v40, 0xbfb8aa3b, v40
	v_mul_f32_e32 v41, 0xbfb8aa3b, v41
	v_mul_f32_e32 v42, 0xbfb8aa3b, v42
	v_mul_f32_e32 v43, 0xbfb8aa3b, v43
	v_exp_f32_e32 v33, v33
	v_exp_f32_e32 v44, v44
	v_exp_f32_e32 v45, v45
	v_exp_f32_e32 v46, v46
	v_exp_f32_e32 v47, v47
	v_exp_f32_e32 v40, v40
	v_exp_f32_e32 v41, v41
	v_exp_f32_e32 v42, v42
	v_exp_f32_e32 v43, v43
	v_fma_f32 v36, v36, v52, v84
	v_fma_f32 v37, v37, v52, v85
	v_fma_f32 v38, v38, v52, v86
	v_fma_f32 v39, v39, v52, v87
	v_add_f32_e32 v32, 1.0, v32
	v_mul_f32_e32 v36, 0xbfb8aa3b, v36
	v_mul_f32_e32 v37, 0xbfb8aa3b, v37
	v_mul_f32_e32 v38, 0xbfb8aa3b, v38
	v_mul_f32_e32 v39, 0xbfb8aa3b, v39
	v_rcp_f32_e32 v57, v32
	v_add_f32_e32 v32, 1.0, v33
	v_fma_f32 v33, v34, v52, v74
	v_exp_f32_e32 v36, v36
	v_exp_f32_e32 v37, v37
	v_exp_f32_e32 v38, v38
	v_exp_f32_e32 v39, v39
	v_add_f32_e32 v44, 1.0, v44
	v_add_f32_e32 v45, 1.0, v45
	v_add_f32_e32 v46, 1.0, v46
	v_add_f32_e32 v47, 1.0, v47
	v_add_f32_e32 v40, 1.0, v40
	v_add_f32_e32 v41, 1.0, v41
	v_add_f32_e32 v42, 1.0, v42
	v_add_f32_e32 v43, 1.0, v43
	v_mul_f32_e32 v33, 0xbfb8aa3b, v33
	v_fma_f32 v34, v35, v52, v75
	v_rcp_f32_e32 v44, v44
	v_rcp_f32_e32 v45, v45
	v_rcp_f32_e32 v46, v46
	v_rcp_f32_e32 v47, v47
	v_rcp_f32_e32 v40, v40
	v_rcp_f32_e32 v41, v41
	v_rcp_f32_e32 v42, v42
	v_rcp_f32_e32 v43, v43
	v_exp_f32_e32 v33, v33
	v_mul_f32_e32 v34, 0xbfb8aa3b, v34
	v_exp_f32_e32 v34, v34
	v_add_f32_e32 v36, 1.0, v36
	v_add_f32_e32 v37, 1.0, v37
	v_add_f32_e32 v38, 1.0, v38
	v_add_f32_e32 v39, 1.0, v39
	v_addc_co_u32_e32 v51, vcc, 0, v163, vcc
	v_rcp_f32_e32 v53, v36
	v_rcp_f32_e32 v54, v37
	v_rcp_f32_e32 v55, v38
	v_rcp_f32_e32 v56, v39
	v_cvt_pk_bf16_f32 v36, v44, v45
	v_cvt_pk_bf16_f32 v37, v46, v47
	v_cvt_pk_bf16_f32 v38, v40, v41
	v_cvt_pk_bf16_f32 v39, v42, v43
	v_rcp_f32_e32 v35, v32
	v_add_f32_e32 v32, 1.0, v33
	flat_store_dwordx4 v[50:51], v[36:39]
	v_cvt_pk_bf16_f32 v33, v55, v56
	s_nop 0
	v_rcp_f32_e32 v36, v32
	v_add_f32_e32 v32, 1.0, v34
	v_rcp_f32_e32 v37, v32
	v_cvt_pk_bf16_f32 v32, v53, v54
	v_cvt_pk_bf16_f32 v34, v57, v35
	v_cvt_pk_bf16_f32 v35, v36, v37
	flat_store_dwordx4 v[48:49], v[32:35] offset:256
	s_nop 0
	s_nop 0
	v_lshl_add_u64 v[32:33], v[162:163], 0, s[16:17]
	v_fmamk_f32 v34, v236, 0x3a800000, v176
	v_rsq_f32_e32 v36, v34
	v_add_co_u32_e32 v34, vcc, s59, v162
	v_fma_f32 v16, v16, v36, v72
	v_fma_f32 v17, v17, v36, v73
	v_mul_f32_e32 v16, 0xbfb8aa3b, v16
	v_fma_f32 v28, v28, v36, v92
	v_fma_f32 v29, v29, v36, v93
	v_fma_f32 v30, v30, v36, v94
	v_fma_f32 v31, v31, v36, v95
	v_fma_f32 v24, v24, v36, v88
	v_fma_f32 v25, v25, v36, v89
	v_fma_f32 v26, v26, v36, v90
	v_fma_f32 v27, v27, v36, v91
	v_mul_f32_e32 v17, 0xbfb8aa3b, v17
	v_exp_f32_e32 v16, v16
	v_mul_f32_e32 v28, 0xbfb8aa3b, v28
	v_mul_f32_e32 v29, 0xbfb8aa3b, v29
	v_mul_f32_e32 v30, 0xbfb8aa3b, v30
	v_mul_f32_e32 v31, 0xbfb8aa3b, v31
	v_mul_f32_e32 v24, 0xbfb8aa3b, v24
	v_mul_f32_e32 v25, 0xbfb8aa3b, v25
	v_mul_f32_e32 v26, 0xbfb8aa3b, v26
	v_mul_f32_e32 v27, 0xbfb8aa3b, v27
	v_exp_f32_e32 v17, v17
	v_exp_f32_e32 v28, v28
	v_exp_f32_e32 v29, v29
	v_exp_f32_e32 v30, v30
	v_exp_f32_e32 v31, v31
	v_exp_f32_e32 v24, v24
	v_exp_f32_e32 v25, v25
	v_exp_f32_e32 v26, v26
	v_exp_f32_e32 v27, v27
	v_fma_f32 v20, v20, v36, v84
	v_fma_f32 v21, v21, v36, v85
	v_fma_f32 v22, v22, v36, v86
	v_fma_f32 v23, v23, v36, v87
	v_add_f32_e32 v16, 1.0, v16
	v_mul_f32_e32 v20, 0xbfb8aa3b, v20
	v_mul_f32_e32 v21, 0xbfb8aa3b, v21
	v_mul_f32_e32 v22, 0xbfb8aa3b, v22
	v_mul_f32_e32 v23, 0xbfb8aa3b, v23
	v_rcp_f32_e32 v41, v16
	v_add_f32_e32 v16, 1.0, v17
	v_fma_f32 v17, v18, v36, v74
	v_exp_f32_e32 v20, v20
	v_exp_f32_e32 v21, v21
; #define PG8_BAR __builtin_amdgcn_s_barrier()
; DI unsigned pk2(float lo, float hi) { typedef float v2f __attribute__((ext_vector_type(2))); typedef __bf16 v2b __attribute__((ext_vector_type(2))); v2f v = {lo, hi}; v2b b = __builtin_convertvector(v, v2b); return __builtin_bit_cast(unsigned, b); }
; DI float sigmoidf_(float v) { return __builtin_amdgcn_rcpf(1.0f + __expf(-v)); }
; template <class Epi, class Sched, bool ALIGN_EPI = false, bool SP2 = false>
; __device__ __forceinline__ void gemm_phase(PG8_LAS unsigned char* lds, const Gemm g, const Sched& S, const Epi& E) {
;     ...
;         cur = nxt; cA = nA; cB = nB; ++ui;
;         if constexpr (ALIGN_EPI) { if (wr == 1) PG8_BAR; }
;     DI void operator()(const f32x4 (&acc)[2][2][4][2], const Unit& u, int wr, int wc, int fr, int fq) const {
;     ...
;                 const int row = row0 + ai * 128 + m * 16; const float rs = row_rstd<16>(P, row, 1.0f / 1024.0f);
; #pragma unroll
;                 for (int bj = 0; bj < 2; ++bj) {
;                     float v[8];
; #pragma unroll
;                     for (int n = 0; n < 2; ++n)
; #pragma unroll
;                         for (int i = 0; i < 4; ++i) v[4 * n + i] = sigmoidf_(acc[ai][bj][m][n][i] * rs + bv[bj][n][i]);
;                     u32x4 w; w.x = pk2(v[0], v[1]); w.y = pk2(v[2], v[3]); w.z = pk2(v[4], v[5]); w.w = pk2(v[6], v[7]);
;                     *(u32x4*)(G + (size_t)row * DM + cw + bj * 128) = w;
;                 }
	v_exp_f32_e32 v22, v22
	v_exp_f32_e32 v23, v23
	v_add_f32_e32 v28, 1.0, v28
	v_add_f32_e32 v29, 1.0, v29
	v_add_f32_e32 v30, 1.0, v30
	v_add_f32_e32 v31, 1.0, v31
	v_add_f32_e32 v24, 1.0, v24
	v_add_f32_e32 v25, 1.0, v25
	v_add_f32_e32 v26, 1.0, v26
	v_add_f32_e32 v27, 1.0, v27
	v_mul_f32_e32 v17, 0xbfb8aa3b, v17
	v_fma_f32 v18, v19, v36, v75
	v_rcp_f32_e32 v28, v28
	v_rcp_f32_e32 v29, v29
	v_rcp_f32_e32 v30, v30
	v_rcp_f32_e32 v31, v31
	v_rcp_f32_e32 v24, v24
	v_rcp_f32_e32 v25, v25
	v_rcp_f32_e32 v26, v26
	v_rcp_f32_e32 v27, v27
	v_exp_f32_e32 v17, v17
	v_mul_f32_e32 v18, 0xbfb8aa3b, v18
	v_exp_f32_e32 v18, v18
	v_add_f32_e32 v20, 1.0, v20
	v_add_f32_e32 v21, 1.0, v21
	v_add_f32_e32 v22, 1.0, v22
	v_add_f32_e32 v23, 1.0, v23
	v_addc_co_u32_e32 v35, vcc, 0, v163, vcc
	v_rcp_f32_e32 v37, v20
	v_rcp_f32_e32 v38, v21
	v_rcp_f32_e32 v39, v22
	v_rcp_f32_e32 v40, v23
	v_cvt_pk_bf16_f32 v20, v28, v29
	v_cvt_pk_bf16_f32 v21, v30, v31
	v_cvt_pk_bf16_f32 v22, v24, v25
	v_cvt_pk_bf16_f32 v23, v26, v27
	v_rcp_f32_e32 v19, v16
	v_add_f32_e32 v16, 1.0, v17
	flat_store_dwordx4 v[34:35], v[20:23]
	v_cvt_pk_bf16_f32 v17, v39, v40
	s_nop 0
	v_rcp_f32_e32 v20, v16
	v_add_f32_e32 v16, 1.0, v18
	v_rcp_f32_e32 v21, v16
	v_cvt_pk_bf16_f32 v16, v37, v38
	v_cvt_pk_bf16_f32 v18, v41, v19
	v_cvt_pk_bf16_f32 v19, v20, v21
	flat_store_dwordx4 v[32:33], v[16:19] offset:256
	s_nop 0
	s_nop 0
	v_lshl_add_u64 v[16:17], v[162:163], 0, s[18:19]
	v_fmamk_f32 v18, v237, 0x3a800000, v176
	v_rsq_f32_e32 v20, v18
	v_add_co_u32_e32 v18, vcc, s60, v162
	v_fma_f32 v0, v0, v20, v72
	v_fma_f32 v1, v1, v20, v73
	v_mul_f32_e32 v0, 0xbfb8aa3b, v0
	v_fma_f32 v12, v12, v20, v92
	v_fma_f32 v13, v13, v20, v93
	v_fma_f32 v14, v14, v20, v94
	v_fmac_f32_e32 v95, v15, v20
	v_fma_f32 v8, v8, v20, v88
	v_fma_f32 v9, v9, v20, v89
	v_fma_f32 v10, v10, v20, v90
	v_fmac_f32_e32 v91, v11, v20
	v_mul_f32_e32 v1, 0xbfb8aa3b, v1
	v_exp_f32_e32 v0, v0
	v_fmac_f32_e32 v87, v7, v20
	v_mul_f32_e32 v7, 0xbfb8aa3b, v12
	v_mul_f32_e32 v11, 0xbfb8aa3b, v13
	v_mul_f32_e32 v12, 0xbfb8aa3b, v14
	v_mul_f32_e32 v13, 0xbfb8aa3b, v95
	v_mul_f32_e32 v8, 0xbfb8aa3b, v8
	v_mul_f32_e32 v9, 0xbfb8aa3b, v9
	v_mul_f32_e32 v10, 0xbfb8aa3b, v10
	v_mul_f32_e32 v14, 0xbfb8aa3b, v91
	v_exp_f32_e32 v1, v1
	v_exp_f32_e32 v7, v7
	v_exp_f32_e32 v11, v11
	v_exp_f32_e32 v12, v12
	v_exp_f32_e32 v13, v13
	v_exp_f32_e32 v8, v8
	v_exp_f32_e32 v9, v9
	v_exp_f32_e32 v10, v10
	v_exp_f32_e32 v14, v14
	v_fma_f32 v4, v4, v20, v84
	v_fma_f32 v5, v5, v20, v85
	v_fma_f32 v6, v6, v20, v86
	v_add_f32_e32 v0, 1.0, v0
	v_mul_f32_e32 v4, 0xbfb8aa3b, v4
	v_mul_f32_e32 v5, 0xbfb8aa3b, v5
	v_mul_f32_e32 v6, 0xbfb8aa3b, v6
	v_rcp_f32_e32 v24, v0
	v_add_f32_e32 v0, 1.0, v1
	v_fma_f32 v1, v2, v20, v74
	v_exp_f32_e32 v4, v4
	v_exp_f32_e32 v5, v5
	v_exp_f32_e32 v6, v6
	v_add_f32_e32 v7, 1.0, v7
	v_add_f32_e32 v11, 1.0, v11
	v_add_f32_e32 v12, 1.0, v12
	v_add_f32_e32 v13, 1.0, v13
	v_add_f32_e32 v8, 1.0, v8
	v_add_f32_e32 v9, 1.0, v9
	v_add_f32_e32 v10, 1.0, v10
	v_add_f32_e32 v14, 1.0, v14
	v_mul_f32_e32 v1, 0xbfb8aa3b, v1
	v_fmac_f32_e32 v75, v3, v20
	v_mul_f32_e32 v15, 0xbfb8aa3b, v87
	v_rcp_f32_e32 v7, v7
	v_rcp_f32_e32 v11, v11
	v_rcp_f32_e32 v12, v12
	v_rcp_f32_e32 v13, v13
	v_rcp_f32_e32 v8, v8
	v_rcp_f32_e32 v9, v9
	v_rcp_f32_e32 v10, v10
	v_rcp_f32_e32 v14, v14
	v_exp_f32_e32 v1, v1
	v_mul_f32_e32 v2, 0xbfb8aa3b, v75
	v_exp_f32_e32 v15, v15
	v_exp_f32_e32 v2, v2
	v_add_f32_e32 v4, 1.0, v4
	v_add_f32_e32 v5, 1.0, v5
	v_add_f32_e32 v6, 1.0, v6
	v_addc_co_u32_e32 v19, vcc, 0, v163, vcc
	v_rcp_f32_e32 v21, v4
	v_rcp_f32_e32 v22, v5
	v_rcp_f32_e32 v23, v6
	v_cvt_pk_bf16_f32 v4, v7, v11
	v_cvt_pk_bf16_f32 v5, v12, v13
	v_cvt_pk_bf16_f32 v6, v8, v9
	v_cvt_pk_bf16_f32 v7, v10, v14
	v_rcp_f32_e32 v3, v0
	v_add_f32_e32 v0, 1.0, v1
	v_add_f32_e32 v15, 1.0, v15
	flat_store_dwordx4 v[18:19], v[4:7]
	v_rcp_f32_e32 v15, v15
	s_andn2_b64 vcc, exec, s[2:3]
	v_rcp_f32_e32 v4, v0
	v_add_f32_e32 v0, 1.0, v2
	v_rcp_f32_e32 v5, v0
	v_cvt_pk_bf16_f32 v0, v21, v22
	v_cvt_pk_bf16_f32 v1, v23, v15
	v_cvt_pk_bf16_f32 v2, v24, v3
	v_cvt_pk_bf16_f32 v3, v4, v5
	s_mov_b64 s[2:3], -1
	flat_store_dwordx4 v[16:17], v[0:3] offset:256
	s_cbranch_vccnz .LBB0_1591
	s_andn2_b64 vcc, exec, s[4:5]
	s_cbranch_vccnz .LBB0_1590
	s_barrier
	s_branch .LBB0_1590
